# attention tile loop: LDS fragment prefetch depth raised from 3 to 4 MFMA operand pairs (fourth slot pair from free registers)
# baseline (speedup 1.0000x reference)
.LBB0_40:
	s_add_i32 s60, s59, 0
	v_add_u32_e32 v144, s60, v196
	ds_read_b128 v[188:191], v144
	ds_read_b128 v[200:203], v197
	v_xad_u32 v144, v196, 32, s60
	ds_read_b128 v[204:207], v144
	v_xor_b32_e32 v199, 32, v197
	ds_read_b128 v[216:219], v199
	v_xad_u32 v144, v196, 64, s60
	ds_read_b128 v[220:223], v144
	v_xor_b32_e32 v199, 64, v197
	ds_read_b128 v[224:227], v199
	v_xor_b32_e32 v144, 0x60, v196
	v_add_u32_e32 v144, s60, v144
	ds_read_b128 v[244:247], v144
	v_xor_b32_e32 v199, 0x60, v197
	ds_read_b128 v[248:251], v199
	s_waitcnt lgkmcnt(6)
	v_mfma_f32_32x32x16_bf16 v[128:143], v[188:191], v[200:203], 0
	v_xor_b32_e32 v144, 0x80, v196
	v_add_u32_e32 v144, s60, v144
	ds_read_b128 v[188:191], v144
	v_xor_b32_e32 v199, 0x80, v197
	ds_read_b128 v[200:203], v199
	s_waitcnt lgkmcnt(6)
	v_mfma_f32_32x32x16_bf16 v[128:143], v[204:207], v[216:219], v[128:143]
	v_xor_b32_e32 v144, 0xa0, v196
	v_add_u32_e32 v144, s60, v144
	ds_read_b128 v[204:207], v144
	v_xor_b32_e32 v199, 0xa0, v197
	ds_read_b128 v[216:219], v199
	s_waitcnt lgkmcnt(6)
	v_mfma_f32_32x32x16_bf16 v[128:143], v[220:223], v[224:227], v[128:143]
	v_xor_b32_e32 v144, 0xc0, v196
	v_add_u32_e32 v144, s60, v144
	ds_read_b128 v[220:223], v144
	v_xor_b32_e32 v199, 0xc0, v197
	ds_read_b128 v[224:227], v199
	s_waitcnt lgkmcnt(6)
	v_mfma_f32_32x32x16_bf16 v[128:143], v[244:247], v[248:251], v[128:143]
	v_xor_b32_e32 v144, 0xe0, v196
	v_add_u32_e32 v144, s60, v144
	ds_read_b128 v[244:247], v144
	v_xor_b32_e32 v199, 0xe0, v197
	ds_read_b128 v[248:251], v199
	s_waitcnt lgkmcnt(6)
	v_mfma_f32_32x32x16_bf16 v[156:171], v[188:191], v[200:203], 0
	v_add_u32_e32 v144, s60, v196
	ds_read_b128 v[188:191], v144 offset:8192
	ds_read_b128 v[200:203], v197
	s_waitcnt lgkmcnt(6)
	v_mfma_f32_32x32x16_bf16 v[156:171], v[204:207], v[216:219], v[156:171]
	v_xad_u32 v144, v196, 32, s60
	ds_read_b128 v[204:207], v144 offset:8192
	v_xor_b32_e32 v199, 32, v197
	ds_read_b128 v[216:219], v199
	v_exp_f32_e32 v128, v128
	v_exp_f32_e32 v129, v129
	v_exp_f32_e32 v130, v130
	v_exp_f32_e32 v131, v131
	v_exp_f32_e32 v132, v132
	s_waitcnt lgkmcnt(6)
	v_mfma_f32_32x32x16_bf16 v[156:171], v[220:223], v[224:227], v[156:171]
	v_xad_u32 v144, v196, 64, s60
	ds_read_b128 v[220:223], v144 offset:8192
	v_xor_b32_e32 v199, 64, v197
	ds_read_b128 v[224:227], v199
	v_exp_f32_e32 v133, v133
	v_exp_f32_e32 v134, v134
	v_exp_f32_e32 v135, v135
	v_exp_f32_e32 v136, v136
	v_exp_f32_e32 v137, v137
	s_waitcnt lgkmcnt(6)
	v_mfma_f32_32x32x16_bf16 v[156:171], v[244:247], v[248:251], v[156:171]
	v_xor_b32_e32 v144, 0x60, v196
	v_add_u32_e32 v144, s60, v144
	ds_read_b128 v[244:247], v144 offset:8192
	v_xor_b32_e32 v199, 0x60, v197
	ds_read_b128 v[248:251], v199
	v_exp_f32_e32 v138, v138
	v_exp_f32_e32 v139, v139
	v_exp_f32_e32 v140, v140
	v_exp_f32_e32 v141, v141
	v_exp_f32_e32 v142, v142
	s_waitcnt lgkmcnt(6)
	v_mfma_f32_32x32x16_bf16 v[172:187], v[188:191], v[200:203], 0
	v_xor_b32_e32 v144, 0x80, v196
	v_add_u32_e32 v144, s60, v144
	ds_read_b128 v[188:191], v144 offset:8192
	v_xor_b32_e32 v199, 0x80, v197
	ds_read_b128 v[200:203], v199
	v_exp_f32_e32 v143, v143
	v_add_f32_e32 v192, v128, v129
	v_add_f32_e32 v193, v130, v131
	v_add_f32_e32 v192, v192, v132
	v_add_f32_e32 v193, v193, v133
	v_add_f32_e32 v192, v192, v134
	v_add_f32_e32 v193, v193, v135
	v_add_f32_e32 v192, v192, v136
	v_add_f32_e32 v193, v193, v137
	v_add_f32_e32 v192, v192, v138
	s_waitcnt lgkmcnt(6)
	v_mfma_f32_32x32x16_bf16 v[172:187], v[204:207], v[216:219], v[172:187]
	v_xor_b32_e32 v144, 0xa0, v196
	v_add_u32_e32 v144, s60, v144
	ds_read_b128 v[204:207], v144 offset:8192
	v_xor_b32_e32 v199, 0xa0, v197
	ds_read_b128 v[216:219], v199
	v_add_f32_e32 v193, v193, v139
	v_add_f32_e32 v192, v192, v140
	v_add_f32_e32 v193, v193, v141
	v_add_f32_e32 v192, v192, v142
	v_add_f32_e32 v193, v193, v143
	v_add_f32_e32 v192, v192, v193
	v_add_f32_e32 v150, v150, v192
	v_cvt_pk_bf16_f32 v128, v128, v129
	v_cvt_pk_bf16_f32 v129, v130, v131
	v_cvt_pk_bf16_f32 v130, v132, v133
	v_cvt_pk_bf16_f32 v131, v134, v135
	s_waitcnt lgkmcnt(6)
	v_mfma_f32_32x32x16_bf16 v[172:187], v[220:223], v[224:227], v[172:187]
	v_xor_b32_e32 v144, 0xc0, v196
	v_add_u32_e32 v144, s60, v144
	ds_read_b128 v[220:223], v144 offset:8192
	v_xor_b32_e32 v199, 0xc0, v197
	ds_read_b128 v[224:227], v199
	v_cvt_pk_bf16_f32 v132, v136, v137
	v_cvt_pk_bf16_f32 v133, v138, v139
	v_cvt_pk_bf16_f32 v134, v140, v141
	v_cvt_pk_bf16_f32 v135, v142, v143
	v_exp_f32_e32 v156, v156
	v_exp_f32_e32 v157, v157
	v_exp_f32_e32 v158, v158
	s_waitcnt lgkmcnt(6)
	v_mfma_f32_32x32x16_bf16 v[172:187], v[244:247], v[248:251], v[172:187]
	v_xor_b32_e32 v144, 0xe0, v196
	v_add_u32_e32 v144, s60, v144
	ds_read_b128 v[244:247], v144 offset:8192
	v_xor_b32_e32 v199, 0xe0, v197
	ds_read_b128 v[248:251], v199
	v_exp_f32_e32 v159, v159
	v_exp_f32_e32 v160, v160
	v_exp_f32_e32 v161, v161
	v_exp_f32_e32 v162, v162
	v_exp_f32_e32 v163, v163
	s_waitcnt lgkmcnt(6)
	v_mfma_f32_32x32x16_bf16 v[228:243], v[188:191], v[200:203], 0
	v_add_u32_e32 v144, s60, v198
	v_xad_u32 v199, v198, 32, s60
	ds_read_b128 v[188:191], v144
	ds_read_b128 v[200:203], v199
	v_exp_f32_e32 v164, v164
	v_exp_f32_e32 v165, v165
	v_exp_f32_e32 v166, v166
	v_exp_f32_e32 v167, v167
	v_exp_f32_e32 v168, v168
	s_waitcnt lgkmcnt(6)
	v_mfma_f32_32x32x16_bf16 v[228:243], v[204:207], v[216:219], v[228:243]
	ds_read_b128 v[204:207], v144 offset:4096
	ds_read_b128 v[216:219], v199 offset:4096
	v_exp_f32_e32 v169, v169
	v_exp_f32_e32 v170, v170
	v_exp_f32_e32 v171, v171
	v_add_f32_e32 v192, v156, v157
	v_add_f32_e32 v193, v158, v159
	v_add_f32_e32 v192, v192, v160
	v_add_f32_e32 v193, v193, v161
	v_add_f32_e32 v192, v192, v162
	s_waitcnt lgkmcnt(6)
	v_mfma_f32_32x32x16_bf16 v[228:243], v[220:223], v[224:227], v[228:243]
	ds_read_b128 v[220:223], v144 offset:8192
	ds_read_b128 v[224:227], v199 offset:8192
	v_add_f32_e32 v193, v193, v163
	v_add_f32_e32 v192, v192, v164
	v_add_f32_e32 v193, v193, v165
	v_add_f32_e32 v192, v192, v166
	v_add_f32_e32 v193, v193, v167
	v_add_f32_e32 v192, v192, v168
	v_add_f32_e32 v193, v193, v169
	v_add_f32_e32 v192, v192, v170
	v_add_f32_e32 v193, v193, v171
	v_add_f32_e32 v192, v192, v193
	v_add_f32_e32 v151, v151, v192
	s_waitcnt lgkmcnt(6)
	v_mfma_f32_32x32x16_bf16 v[228:243], v[244:247], v[248:251], v[228:243]
	ds_read_b128 v[244:247], v144 offset:12288
	ds_read_b128 v[248:251], v199 offset:12288
	v_cvt_pk_bf16_f32 v156, v156, v157
	v_cvt_pk_bf16_f32 v157, v158, v159
	v_cvt_pk_bf16_f32 v158, v160, v161
	v_cvt_pk_bf16_f32 v159, v162, v163
	v_cvt_pk_bf16_f32 v160, v164, v165
	v_cvt_pk_bf16_f32 v161, v166, v167
	v_cvt_pk_bf16_f32 v162, v168, v169
	v_cvt_pk_bf16_f32 v163, v170, v171
	v_exp_f32_e32 v172, v172
	s_waitcnt lgkmcnt(6)
	v_mfma_f32_32x32x16_bf16 v[112:127], v[188:191], v[128:131], v[112:127]
	v_exp_f32_e32 v173, v173
	v_exp_f32_e32 v174, v174
	v_exp_f32_e32 v175, v175
	v_exp_f32_e32 v176, v176
	v_mfma_f32_32x32x16_bf16 v[96:111], v[188:191], v[156:159], v[96:111]
	v_exp_f32_e32 v177, v177
	v_exp_f32_e32 v178, v178
	v_exp_f32_e32 v179, v179
	v_exp_f32_e32 v180, v180
	v_mfma_f32_32x32x16_bf16 v[112:127], v[200:203], v[132:135], v[112:127]
	v_exp_f32_e32 v181, v181
	v_exp_f32_e32 v182, v182
	v_exp_f32_e32 v183, v183
	v_exp_f32_e32 v184, v184
	v_mfma_f32_32x32x16_bf16 v[96:111], v[200:203], v[160:163], v[96:111]
	v_xad_u32 v144, v198, 64, s60
	v_xor_b32_e32 v199, 0x60, v198
	v_add_u32_e32 v199, s60, v199
	ds_read_b128 v[188:191], v144
	ds_read_b128 v[200:203], v199
	v_exp_f32_e32 v185, v185
	v_exp_f32_e32 v186, v186
	v_exp_f32_e32 v187, v187
	v_add_f32_e32 v192, v172, v173
	v_add_f32_e32 v193, v174, v175
	v_add_f32_e32 v192, v192, v176
	s_waitcnt lgkmcnt(6)
	v_mfma_f32_32x32x16_bf16 v[80:95], v[204:207], v[128:131], v[80:95]
	v_add_f32_e32 v193, v193, v177
	v_add_f32_e32 v192, v192, v178
	v_add_f32_e32 v193, v193, v179
	v_add_f32_e32 v192, v192, v180
	v_add_f32_e32 v193, v193, v181
	v_add_f32_e32 v192, v192, v182
	v_add_f32_e32 v193, v193, v183
	v_add_f32_e32 v192, v192, v184
	v_add_f32_e32 v193, v193, v185
	v_mfma_f32_32x32x16_bf16 v[64:79], v[204:207], v[156:159], v[64:79]
	v_add_f32_e32 v192, v192, v186
	v_add_f32_e32 v193, v193, v187
	v_add_f32_e32 v192, v192, v193
	v_add_f32_e32 v150, v150, v192
	v_cvt_pk_bf16_f32 v172, v172, v173
	v_cvt_pk_bf16_f32 v173, v174, v175
	v_cvt_pk_bf16_f32 v174, v176, v177
	v_cvt_pk_bf16_f32 v175, v178, v179
	v_cvt_pk_bf16_f32 v176, v180, v181
	v_mfma_f32_32x32x16_bf16 v[80:95], v[216:219], v[132:135], v[80:95]
	v_cvt_pk_bf16_f32 v177, v182, v183
	v_cvt_pk_bf16_f32 v178, v184, v185
	v_cvt_pk_bf16_f32 v179, v186, v187
	v_exp_f32_e32 v228, v228
	v_exp_f32_e32 v229, v229
	v_exp_f32_e32 v230, v230
	v_mfma_f32_32x32x16_bf16 v[64:79], v[216:219], v[160:163], v[64:79]
	ds_read_b128 v[204:207], v144 offset:4096
	ds_read_b128 v[216:219], v199 offset:4096
	v_exp_f32_e32 v231, v231
	v_exp_f32_e32 v232, v232
	v_exp_f32_e32 v233, v233
	v_exp_f32_e32 v234, v234
	s_waitcnt lgkmcnt(6)
	v_mfma_f32_32x32x16_bf16 v[48:63], v[220:223], v[128:131], v[48:63]
	v_exp_f32_e32 v235, v235
	v_exp_f32_e32 v236, v236
	v_exp_f32_e32 v237, v237
	v_exp_f32_e32 v238, v238
	v_mfma_f32_32x32x16_bf16 v[32:47], v[220:223], v[156:159], v[32:47]
	v_exp_f32_e32 v239, v239
	v_exp_f32_e32 v240, v240
	v_exp_f32_e32 v241, v241
	v_exp_f32_e32 v242, v242
	v_mfma_f32_32x32x16_bf16 v[48:63], v[224:227], v[132:135], v[48:63]
	v_exp_f32_e32 v243, v243
	v_add_f32_e32 v192, v228, v229
	v_add_f32_e32 v193, v230, v231
	v_add_f32_e32 v192, v192, v232
	v_add_f32_e32 v193, v193, v233
	v_add_f32_e32 v192, v192, v234
	v_add_f32_e32 v193, v193, v235
	v_add_f32_e32 v192, v192, v236
	v_mfma_f32_32x32x16_bf16 v[32:47], v[224:227], v[160:163], v[32:47]
	ds_read_b128 v[220:223], v144 offset:8192
	ds_read_b128 v[224:227], v199 offset:8192
	v_add_f32_e32 v193, v193, v237
	v_add_f32_e32 v192, v192, v238
	v_add_f32_e32 v193, v193, v239
	v_add_f32_e32 v192, v192, v240
	v_add_f32_e32 v193, v193, v241
	v_add_f32_e32 v192, v192, v242
	v_add_f32_e32 v193, v193, v243
	v_add_f32_e32 v192, v192, v193
	v_add_f32_e32 v151, v151, v192
	s_waitcnt lgkmcnt(6)
	v_mfma_f32_32x32x16_bf16 v[16:31], v[244:247], v[128:131], v[16:31]
	v_cvt_pk_bf16_f32 v228, v228, v229
	v_cvt_pk_bf16_f32 v229, v230, v231
	v_cvt_pk_bf16_f32 v230, v232, v233
	v_cvt_pk_bf16_f32 v231, v234, v235
	v_cvt_pk_bf16_f32 v232, v236, v237
	v_cvt_pk_bf16_f32 v233, v238, v239
	v_cvt_pk_bf16_f32 v234, v240, v241
	v_cvt_pk_bf16_f32 v235, v242, v243
	v_mfma_f32_32x32x16_bf16 v[0:15], v[244:247], v[156:159], v[0:15]
	v_mfma_f32_32x32x16_bf16 v[16:31], v[248:251], v[132:135], v[16:31]
	v_mfma_f32_32x32x16_bf16 v[0:15], v[248:251], v[160:163], v[0:15]
	ds_read_b128 v[244:247], v144 offset:12288
	ds_read_b128 v[248:251], v199 offset:12288
	s_waitcnt lgkmcnt(6)
	v_mfma_f32_32x32x16_bf16 v[112:127], v[188:191], v[172:175], v[112:127]
	v_mfma_f32_32x32x16_bf16 v[96:111], v[188:191], v[228:231], v[96:111]
	v_mfma_f32_32x32x16_bf16 v[112:127], v[200:203], v[176:179], v[112:127]
	v_mfma_f32_32x32x16_bf16 v[96:111], v[200:203], v[232:235], v[96:111]
	s_waitcnt lgkmcnt(4)
	v_mfma_f32_32x32x16_bf16 v[80:95], v[204:207], v[172:175], v[80:95]
	v_mfma_f32_32x32x16_bf16 v[64:79], v[204:207], v[228:231], v[64:79]
	v_mfma_f32_32x32x16_bf16 v[80:95], v[216:219], v[176:179], v[80:95]
	v_mfma_f32_32x32x16_bf16 v[64:79], v[216:219], v[232:235], v[64:79]
	s_waitcnt lgkmcnt(2)
	v_mfma_f32_32x32x16_bf16 v[48:63], v[220:223], v[172:175], v[48:63]
	v_mfma_f32_32x32x16_bf16 v[32:47], v[220:223], v[228:231], v[32:47]
	v_mfma_f32_32x32x16_bf16 v[48:63], v[224:227], v[176:179], v[48:63]
	v_mfma_f32_32x32x16_bf16 v[32:47], v[224:227], v[232:235], v[32:47]
	s_waitcnt lgkmcnt(0)
	v_mfma_f32_32x32x16_bf16 v[16:31], v[244:247], v[172:175], v[16:31]
	v_mfma_f32_32x32x16_bf16 v[0:15], v[244:247], v[228:231], v[0:15]
	v_mfma_f32_32x32x16_bf16 v[16:31], v[248:251], v[176:179], v[16:31]
	v_mfma_f32_32x32x16_bf16 v[0:15], v[248:251], v[232:235], v[0:15]
	s_mov_b64 s[92:93], -1
	s_and_b64 vcc, exec, s[86:87]
	s_cbranch_vccnz .LBB0_38
